# baseline (speedup 1.0000x reference)
;     __device__ __forceinline__ unsigned* bar() const { return (unsigned*)(ws + OFF_bar); }
; DEV unsigned xb_ld(unsigned* p)              { return __hip_atomic_load(p, __ATOMIC_RELAXED, __HIP_MEMORY_SCOPE_AGENT); }
; DEV unsigned xb_add(unsigned* p, unsigned v) { return __hip_atomic_fetch_add(p, v, __ATOMIC_RELAXED, __HIP_MEMORY_SCOPE_AGENT); }
; #define XB_SPIN(cond, bar) do { unsigned _sp = 0; while (cond) { __builtin_amdgcn_s_sleep(1); \
;     if ((++_sp & 255u) == 0u) { if (xb_ld(&(bar)[XB_TMO])) break; if (_sp > XB_SPIN_CAP) { atomicAdd(&(bar)[XB_TMO], 1u); break; } } } } while (0)
; DEV void xcd_barrier(const XcdBarrier& b) {
;     ...
;             else XB_SPIN(xb_ld(&bar[XB_TOPGEN]) == tg, bar);
;             __builtin_amdgcn_fence(__ATOMIC_ACQUIRE, "agent");
;             xb_add(&bar[XB_XGEN(b.x)], 1u);
;             asm volatile("s_waitcnt vmcnt(0)" ::: "memory");
;         } else {
;             XB_SPIN(xb_ld(&bar[XB_XGEN(b.x)]) == gen, bar);
.LBB0_2784:
	s_and_b32 s12, s16, 0xff
	s_mov_b64 s[10:11], -1
	s_cmp_lg_u32 s12, 0
	s_mov_b64 s[14:15], -1
	s_sleep 0
	s_cbranch_scc0 .LBB0_2787
	s_and_b64 vcc, exec, s[14:15]
	s_cbranch_vccz .LBB0_2783
